# all three GEMM K-loops: saddr LDS-DMA (no VALU in load segments), s_setprio and post-barrier lgkmcnt removed
# speedup vs baseline: 1.0090x; 1.0021x over previous
.LBB0_202:
	s_add_u32 s20, s14, 0x31400000
	s_addc_u32 s21, s15, 0
	s_lshl_b64 s[4:5], s[36:37], 3
	s_add_u32 s4, s14, s4
	v_bfe_u32 v201, v6, 4, 2
	s_addc_u32 s5, s15, s5
	v_and_b32_e32 v200, 15, v6
	v_lshlrev_b32_e32 v23, 4, v201
	v_lshlrev_b32_e32 v24, 2, v6
	s_add_i32 s51, s33, 0x18000
	s_and_b32 s24, s22, 3
	v_lshl_or_b32 v23, v200, 6, v23
	s_lshl_b32 s14, s23, 13
	v_and_b32_e32 v24, 32, v24
	v_lshl_add_u64 v[14:15], v[14:15], 0, s[82:83]
	s_mov_b32 m0, s51
	s_add_i32 s52, s33, 0x1a000
	s_lshl_b32 s50, s23, 6
	v_bitop3_b32 v25, v23, s14, v24 bitop3:0xde
	s_lshl_b32 s25, s24, 5
	s_lshl_b32 s14, s24, 12
	s_waitcnt vmcnt(2)
	s_barrier
	global_load_lds_dwordx4 v[14:15], off
	v_lshl_add_u64 v[12:13], v[12:13], 0, s[82:83]
	s_mov_b32 m0, s52
	s_add_i32 s53, s33, 0x8000
	s_add_i32 s54, s33, 0xa000
	v_bitop3_b32 v203, v23, s14, v24 bitop3:0xde
	global_load_lds_dwordx4 v[12:13], off
	v_lshl_add_u64 v[8:9], v[8:9], 0, s[82:83]
	s_mov_b32 m0, s53
	s_add_u32 s14, s6, 0x80080
	global_load_lds_dwordx4 v[8:9], off
	v_lshl_add_u64 v[8:9], v[10:11], 0, s[82:83]
	s_mov_b32 m0, s54
	s_addc_u32 s15, s7, 0
	s_add_i32 s55, s33, 0x1c000
	global_load_lds_dwordx4 v[8:9], off
	v_lshl_add_u64 v[8:9], s[14:15], 0, v[4:5]
	s_mov_b32 m0, s55
	s_add_i32 s56, s33, 0x1e000
	global_load_lds_dwordx4 v[8:9], off
	v_lshl_add_u64 v[8:9], s[14:15], 0, v[2:3]
	s_mov_b32 m0, s56
	s_cmp_lt_u32 s22, 4
	global_load_lds_dwordx4 v[8:9], off
	v_ashrrev_i32_e32 v9, 5, v6
	v_lshl_add_u64 v[6:7], v[6:7], 3, s[4:5]
	v_lshl_add_u64 v[170:171], v[6:7], 0, s[72:73]
	v_lshlrev_b32_e32 v6, 15, v21
	v_and_b32_e32 v6, 0xffff0000, v6
	v_lshl_add_u32 v6, v20, 12, v6
	v_and_b32_e32 v7, 1, v21
	v_lshl_or_b32 v6, v7, 6, v6
	v_lshlrev_b32_e32 v8, 4, v16
	v_lshl_add_u32 v172, v22, 1, v6
	v_lshlrev_b32_e32 v6, 15, v17
	v_and_or_b32 v8, v8, 16, v200
	v_readlane_b32 s26, v255, 29
	v_lshlrev_b32_e32 v9, 2, v9
	v_and_b32_e32 v6, 0xffff0000, v6
	s_waitcnt vmcnt(6)
	s_cselect_b64 s[14:15], -1, 0
	v_lshl_add_u32 v8, v8, 5, s26
	v_and_b32_e32 v9, -16, v9
	v_lshlrev_b32_e32 v10, 2, v201
	s_lshl_b32 s22, s23, 9
	s_lshl_b32 s23, s24, 2
	v_lshl_add_u32 v6, v18, 12, v6
	v_and_b32_e32 v7, 1, v17
	v_add3_u32 v204, v8, v9, v10
	s_add_i32 s22, s26, s22
	v_lshlrev_b32_e32 v8, 5, v200
	s_add_i32 s57, s23, 0
	v_lshl_or_b32 v6, v7, 6, v6
	v_readlane_b32 s4, v255, 30
	v_or_b32_e32 v202, s50, v200
	s_add_i32 s57, s57, 0x23000
	s_waitcnt lgkmcnt(0)
	s_ashr_i32 s58, s49, 31
	v_lshl_or_b32 v205, v201, 3, s25
	v_add_u32_e32 v173, 0x10000, v203
	v_lshl_add_u32 v174, v19, 1, v6
	v_mov_b32_e32 v175, v5
	s_mov_b32 s59, 0
	v_mov_b64_e32 v[176:177], 0
	v_add_u32_e32 v212, s22, v8
	s_lshl_b32 s60, s25, 2
	v_add_u32_e32 v213, 0, v25
	v_readlane_b32 s61, v255, 16
	s_mov_b32 s30, s4
	s_barrier
	v_readlane_b32 s5, v255, 31
	s_branch .LBB0_205

.LBB0_208:
	s_mov_b32 m0, s51
	s_add_u32 s66, s34, 0x80
	s_addc_u32 s67, s35, 0
	ds_read_b128 v[188:191], v213 offset:49152
	ds_read_b128 v[192:195], v213 offset:50176
	ds_read_b128 v[196:199], v213 offset:51200
	ds_read_b128 v[206:209], v213 offset:52224
	ds_read_b128 v[214:217], v213 offset:53248
	ds_read_b128 v[218:221], v213 offset:54272
	ds_read_b128 v[222:225], v213 offset:55296
	ds_read_b128 v[226:229], v213 offset:56320
	global_load_lds_dwordx4 v4, s[66:67]
	s_mov_b32 m0, s52
	s_add_u32 s6, s34, 0x80080
	s_addc_u32 s7, s35, 0
	global_load_lds_dwordx4 v2, s[66:67]
	s_mov_b32 m0, s55
	s_add_u32 s98, s38, 0xfff80080
	s_addc_u32 s99, s39, -1
	global_load_lds_dwordx4 v4, s[6:7]
	s_mov_b32 m0, s56
	s_nop 0
	global_load_lds_dwordx4 v2, s[6:7]
	s_mov_b32 m0, s53
	s_nop 0
	global_load_lds_dwordx4 v168, s[98:99]
	s_mov_b32 m0, s54
	s_nop 0
	global_load_lds_dwordx4 v166, s[98:99]
	s_waitcnt vmcnt(8)
	s_waitcnt lgkmcnt(0)
	s_barrier
	v_mfma_f32_16x16x32_bf16 v[18:21], v[158:161], v[188:191], v[18:21]
	v_mfma_f32_16x16x32_bf16 v[26:29], v[162:165], v[188:191], v[26:29]
	v_mfma_f32_16x16x32_bf16 v[34:37], v[158:161], v[196:199], v[34:37]
	v_mfma_f32_16x16x32_bf16 v[42:45], v[162:165], v[196:199], v[42:45]
	v_mfma_f32_16x16x32_bf16 v[180:183], v[158:161], v[214:217], v[50:53]
	v_mfma_f32_16x16x32_bf16 v[184:187], v[162:165], v[214:217], v[58:61]
	v_mfma_f32_16x16x32_bf16 v[158:161], v[158:161], v[222:225], v[62:65]
	v_mfma_f32_16x16x32_bf16 v[162:165], v[162:165], v[222:225], v[66:69]
	v_mfma_f32_16x16x32_bf16 v[66:69], v[150:153], v[192:195], v[18:21]
	v_mfma_f32_16x16x32_bf16 v[62:65], v[154:157], v[192:195], v[26:29]
	v_mfma_f32_16x16x32_bf16 v[58:61], v[150:153], v[206:209], v[34:37]
	v_mfma_f32_16x16x32_bf16 v[50:53], v[154:157], v[206:209], v[42:45]
	v_mfma_f32_16x16x32_bf16 v[42:45], v[150:153], v[218:221], v[180:183]
	v_mfma_f32_16x16x32_bf16 v[34:37], v[154:157], v[218:221], v[184:187]
	v_mfma_f32_16x16x32_bf16 v[26:29], v[150:153], v[226:229], v[158:161]
	v_mfma_f32_16x16x32_bf16 v[18:21], v[154:157], v[226:229], v[162:165]
	v_mfma_f32_16x16x32_bf16 v[6:9], v[142:145], v[188:191], v[6:9]
	v_mfma_f32_16x16x32_bf16 v[10:13], v[146:149], v[188:191], v[10:13]
	v_mfma_f32_16x16x32_bf16 v[14:17], v[142:145], v[196:199], v[14:17]
	v_mfma_f32_16x16x32_bf16 v[22:25], v[146:149], v[196:199], v[22:25]
	v_mfma_f32_16x16x32_bf16 v[150:153], v[142:145], v[214:217], v[30:33]
	v_mfma_f32_16x16x32_bf16 v[154:157], v[146:149], v[214:217], v[38:41]
	v_mfma_f32_16x16x32_bf16 v[142:145], v[142:145], v[222:225], v[46:49]
	v_mfma_f32_16x16x32_bf16 v[146:149], v[146:149], v[222:225], v[54:57]
	v_mfma_f32_16x16x32_bf16 v[54:57], v[134:137], v[192:195], v[6:9]
	v_mfma_f32_16x16x32_bf16 v[46:49], v[138:141], v[192:195], v[10:13]
	v_mfma_f32_16x16x32_bf16 v[38:41], v[134:137], v[206:209], v[14:17]
	v_mfma_f32_16x16x32_bf16 v[30:33], v[138:141], v[206:209], v[22:25]
	v_mfma_f32_16x16x32_bf16 v[22:25], v[134:137], v[218:221], v[150:153]
	v_mfma_f32_16x16x32_bf16 v[14:17], v[138:141], v[218:221], v[154:157]
	v_mfma_f32_16x16x32_bf16 v[10:13], v[134:137], v[226:229], v[142:145]
	v_mfma_f32_16x16x32_bf16 v[6:9], v[138:141], v[226:229], v[146:149]
	s_barrier
	s_add_i32 s65, s65, 2
	s_add_u32 s8, s8, 0x100
	s_addc_u32 s9, s9, 0
	s_add_u32 s31, s31, 0x100
	s_addc_u32 s64, s64, 0
	s_cmp_gt_u32 s65, 29
	s_cbranch_scc1 .LBB0_213
.LBB0_209:
	s_cmp_eq_u32 s65, 28
	s_cselect_b64 s[34:35], -1, 0
	s_and_b64 s[38:39], s[34:35], s[14:15]
	s_andn2_b64 s[6:7], exec, s[38:39]
	s_andn2_b64 vcc, exec, s[38:39]
	s_cbranch_vccnz .LBB0_211
	global_load_dwordx2 v[176:177], v[178:179], off
.LBB0_211:
	s_add_u32 s38, s8, 0xfff80080
	s_addc_u32 s39, s9, -1
	s_and_b64 s[34:35], s[34:35], exec
	s_cselect_b32 s39, s25, s39
	s_cselect_b32 s38, s62, s38
	s_cselect_b32 s35, s23, s64
	s_cselect_b32 s34, s63, s31
	s_add_i32 s66, 0, 0x10000
	s_add_i32 s68, 0, 0x14000
	ds_read_b128 v[134:137], v173
	ds_read_b128 v[138:141], v173 offset:1024
	ds_read_b128 v[142:145], v173 offset:2048
	ds_read_b128 v[146:149], v173 offset:3072
	ds_read_b128 v[150:153], v173 offset:16384
	ds_read_b128 v[154:157], v173 offset:17408
	ds_read_b128 v[158:161], v173 offset:18432
	ds_read_b128 v[162:165], v173 offset:19456
	s_add_i32 m0, s33, 0xc000
	ds_read_b128 v[180:183], v213
	ds_read_b128 v[184:187], v213 offset:1024
	ds_read_b128 v[188:191], v213 offset:2048
	ds_read_b128 v[192:195], v213 offset:3072
	ds_read_b128 v[196:199], v213 offset:4096
	ds_read_b128 v[206:209], v213 offset:5120
	ds_read_b128 v[214:217], v213 offset:6144
	ds_read_b128 v[218:221], v213 offset:7168
	global_load_lds_dwordx4 v172, s[8:9]
	s_add_i32 m0, s33, 0xe000
	s_nop 0
	global_load_lds_dwordx4 v174, s[8:9]
	s_waitcnt vmcnt(8)
	s_waitcnt lgkmcnt(0)
	s_barrier
	v_mfma_f32_16x16x32_bf16 v[130:133], v[134:137], v[180:183], v[130:133]
	v_mfma_f32_16x16x32_bf16 v[126:129], v[142:145], v[180:183], v[126:129]
	v_mfma_f32_16x16x32_bf16 v[122:125], v[134:137], v[188:191], v[122:125]
	v_mfma_f32_16x16x32_bf16 v[114:117], v[142:145], v[188:191], v[114:117]
	v_mfma_f32_16x16x32_bf16 v[106:109], v[134:137], v[196:199], v[106:109]
	v_mfma_f32_16x16x32_bf16 v[98:101], v[142:145], v[196:199], v[98:101]
	v_mfma_f32_16x16x32_bf16 v[90:93], v[134:137], v[214:217], v[90:93]
	v_mfma_f32_16x16x32_bf16 v[82:85], v[142:145], v[214:217], v[82:85]
	v_mfma_f32_16x16x32_bf16 v[130:133], v[138:141], v[184:187], v[130:133]
	v_mfma_f32_16x16x32_bf16 v[126:129], v[146:149], v[184:187], v[126:129]
	v_mfma_f32_16x16x32_bf16 v[122:125], v[138:141], v[192:195], v[122:125]
	v_mfma_f32_16x16x32_bf16 v[114:117], v[146:149], v[192:195], v[114:117]
	v_mfma_f32_16x16x32_bf16 v[106:109], v[138:141], v[206:209], v[106:109]
	v_mfma_f32_16x16x32_bf16 v[98:101], v[146:149], v[206:209], v[98:101]
	v_mfma_f32_16x16x32_bf16 v[90:93], v[138:141], v[218:221], v[90:93]
	v_mfma_f32_16x16x32_bf16 v[82:85], v[146:149], v[218:221], v[82:85]
	v_mfma_f32_16x16x32_bf16 v[118:121], v[150:153], v[180:183], v[118:121]
	v_mfma_f32_16x16x32_bf16 v[110:113], v[158:161], v[180:183], v[110:113]
	v_mfma_f32_16x16x32_bf16 v[102:105], v[150:153], v[188:191], v[102:105]
	v_mfma_f32_16x16x32_bf16 v[94:97], v[158:161], v[188:191], v[94:97]
	v_mfma_f32_16x16x32_bf16 v[86:89], v[150:153], v[196:199], v[86:89]
	v_mfma_f32_16x16x32_bf16 v[78:81], v[158:161], v[196:199], v[78:81]
	v_mfma_f32_16x16x32_bf16 v[74:77], v[150:153], v[214:217], v[74:77]
	v_mfma_f32_16x16x32_bf16 v[70:73], v[158:161], v[214:217], v[70:73]
	v_mfma_f32_16x16x32_bf16 v[118:121], v[154:157], v[184:187], v[118:121]
	v_mfma_f32_16x16x32_bf16 v[110:113], v[162:165], v[184:187], v[110:113]
	v_mfma_f32_16x16x32_bf16 v[102:105], v[154:157], v[192:195], v[102:105]
	v_mfma_f32_16x16x32_bf16 v[94:97], v[162:165], v[192:195], v[94:97]
	v_mfma_f32_16x16x32_bf16 v[86:89], v[154:157], v[206:209], v[86:89]
	v_mfma_f32_16x16x32_bf16 v[78:81], v[162:165], v[206:209], v[78:81]
	v_mfma_f32_16x16x32_bf16 v[74:77], v[154:157], v[218:221], v[74:77]
	v_mfma_f32_16x16x32_bf16 v[70:73], v[162:165], v[218:221], v[70:73]
	s_barrier
	s_add_i32 s66, s66, s45
	s_mov_b32 m0, s66
	ds_read_b128 v[188:191], v213 offset:16384
	ds_read_b128 v[192:195], v213 offset:17408
	ds_read_b128 v[196:199], v213 offset:18432
	ds_read_b128 v[206:209], v213 offset:19456
	ds_read_b128 v[214:217], v213 offset:20480
	ds_read_b128 v[218:221], v213 offset:21504
	ds_read_b128 v[222:225], v213 offset:22528
	ds_read_b128 v[226:229], v213 offset:23552
	global_load_lds_dwordx4 v4, s[34:35]
	s_add_i32 m0, s66, 0x2000
	s_add_u32 s66, s34, 0x80000
	s_addc_u32 s67, s35, 0
	global_load_lds_dwordx4 v2, s[34:35]
	s_add_i32 s68, s68, s45
	s_mov_b32 m0, s68
	s_nop 0
	global_load_lds_dwordx4 v4, s[66:67]
	s_add_i32 m0, s68, 0x2000
	s_nop 0
	global_load_lds_dwordx4 v2, s[66:67]
	s_mov_b32 m0, s33
	s_nop 0
	global_load_lds_dwordx4 v168, s[38:39]
	s_mov_b32 m0, s46
	s_nop 0
	global_load_lds_dwordx4 v166, s[38:39]
	s_waitcnt vmcnt(8)
	s_waitcnt lgkmcnt(0)
	s_barrier
	v_mfma_f32_16x16x32_bf16 v[66:69], v[134:137], v[188:191], v[66:69]
	v_mfma_f32_16x16x32_bf16 v[62:65], v[142:145], v[188:191], v[62:65]
	v_mfma_f32_16x16x32_bf16 v[58:61], v[134:137], v[196:199], v[58:61]
	v_mfma_f32_16x16x32_bf16 v[50:53], v[142:145], v[196:199], v[50:53]
	v_mfma_f32_16x16x32_bf16 v[248:251], v[134:137], v[214:217], v[42:45]
	v_mfma_f32_16x16x32_bf16 v[236:239], v[142:145], v[214:217], v[34:37]
	v_mfma_f32_16x16x32_bf16 v[134:137], v[134:137], v[222:225], v[26:29]
	v_mfma_f32_16x16x32_bf16 v[142:145], v[142:145], v[222:225], v[18:21]
	v_mfma_f32_16x16x32_bf16 v[18:21], v[138:141], v[192:195], v[66:69]
	v_mfma_f32_16x16x32_bf16 v[26:29], v[146:149], v[192:195], v[62:65]
	v_mfma_f32_16x16x32_bf16 v[34:37], v[138:141], v[206:209], v[58:61]
	v_mfma_f32_16x16x32_bf16 v[42:45], v[146:149], v[206:209], v[50:53]
	v_mfma_f32_16x16x32_bf16 v[50:53], v[138:141], v[218:221], v[248:251]
	v_mfma_f32_16x16x32_bf16 v[58:61], v[146:149], v[218:221], v[236:239]
	v_mfma_f32_16x16x32_bf16 v[62:65], v[138:141], v[226:229], v[134:137]
	v_mfma_f32_16x16x32_bf16 v[66:69], v[146:149], v[226:229], v[142:145]
	v_mfma_f32_16x16x32_bf16 v[54:57], v[150:153], v[188:191], v[54:57]
	v_mfma_f32_16x16x32_bf16 v[46:49], v[158:161], v[188:191], v[46:49]
	v_mfma_f32_16x16x32_bf16 v[38:41], v[150:153], v[196:199], v[38:41]
	v_mfma_f32_16x16x32_bf16 v[30:33], v[158:161], v[196:199], v[30:33]
	v_mfma_f32_16x16x32_bf16 v[134:137], v[150:153], v[214:217], v[22:25]
	v_mfma_f32_16x16x32_bf16 v[138:141], v[158:161], v[214:217], v[14:17]
	v_mfma_f32_16x16x32_bf16 v[142:145], v[150:153], v[222:225], v[10:13]
	v_mfma_f32_16x16x32_bf16 v[146:149], v[158:161], v[222:225], v[6:9]
	v_mfma_f32_16x16x32_bf16 v[6:9], v[154:157], v[192:195], v[54:57]
	v_mfma_f32_16x16x32_bf16 v[10:13], v[162:165], v[192:195], v[46:49]
	v_mfma_f32_16x16x32_bf16 v[14:17], v[154:157], v[206:209], v[38:41]
	v_mfma_f32_16x16x32_bf16 v[22:25], v[162:165], v[206:209], v[30:33]
	v_mfma_f32_16x16x32_bf16 v[30:33], v[154:157], v[218:221], v[134:137]
	v_mfma_f32_16x16x32_bf16 v[38:41], v[162:165], v[218:221], v[138:141]
	v_mfma_f32_16x16x32_bf16 v[46:49], v[154:157], v[226:229], v[142:145]
	v_mfma_f32_16x16x32_bf16 v[54:57], v[162:165], v[226:229], v[146:149]
	s_barrier
	ds_read_b128 v[158:161], v173 offset:32768
	ds_read_b128 v[150:153], v173 offset:33792
	ds_read_b128 v[162:165], v173 offset:34816
	ds_read_b128 v[154:157], v173 offset:35840
	ds_read_b128 v[142:145], v173 offset:49152
	ds_read_b128 v[134:137], v173 offset:50176
	ds_read_b128 v[146:149], v173 offset:51200
	ds_read_b128 v[138:141], v173 offset:52224
	s_add_u32 s38, s38, 0x80000
	s_addc_u32 s39, s39, 0
	s_mov_b32 m0, s47
	ds_read_b128 v[188:191], v213 offset:32768
	ds_read_b128 v[192:195], v213 offset:33792
	ds_read_b128 v[196:199], v213 offset:34816
	ds_read_b128 v[206:209], v213 offset:35840
	ds_read_b128 v[214:217], v213 offset:36864
	ds_read_b128 v[218:221], v213 offset:37888
	ds_read_b128 v[222:225], v213 offset:38912
	ds_read_b128 v[226:229], v213 offset:39936
	global_load_lds_dwordx4 v168, s[38:39]
	s_mov_b32 m0, s48
	s_nop 0
	global_load_lds_dwordx4 v166, s[38:39]
	s_waitcnt vmcnt(8)
	s_waitcnt lgkmcnt(0)
	s_barrier
	v_mfma_f32_16x16x32_bf16 v[130:133], v[158:161], v[188:191], v[130:133]
	v_mfma_f32_16x16x32_bf16 v[126:129], v[162:165], v[188:191], v[126:129]
	v_mfma_f32_16x16x32_bf16 v[122:125], v[158:161], v[196:199], v[122:125]
	v_mfma_f32_16x16x32_bf16 v[114:117], v[162:165], v[196:199], v[114:117]
	v_mfma_f32_16x16x32_bf16 v[106:109], v[158:161], v[214:217], v[106:109]
	v_mfma_f32_16x16x32_bf16 v[98:101], v[162:165], v[214:217], v[98:101]
	v_mfma_f32_16x16x32_bf16 v[90:93], v[158:161], v[222:225], v[90:93]
	v_mfma_f32_16x16x32_bf16 v[82:85], v[162:165], v[222:225], v[82:85]
	v_mfma_f32_16x16x32_bf16 v[130:133], v[150:153], v[192:195], v[130:133]
	v_mfma_f32_16x16x32_bf16 v[126:129], v[154:157], v[192:195], v[126:129]
	v_mfma_f32_16x16x32_bf16 v[122:125], v[150:153], v[206:209], v[122:125]
	v_mfma_f32_16x16x32_bf16 v[114:117], v[154:157], v[206:209], v[114:117]
	v_mfma_f32_16x16x32_bf16 v[106:109], v[150:153], v[218:221], v[106:109]
	v_mfma_f32_16x16x32_bf16 v[98:101], v[154:157], v[218:221], v[98:101]
	v_mfma_f32_16x16x32_bf16 v[90:93], v[150:153], v[226:229], v[90:93]
	v_mfma_f32_16x16x32_bf16 v[82:85], v[154:157], v[226:229], v[82:85]
	v_mfma_f32_16x16x32_bf16 v[118:121], v[142:145], v[188:191], v[118:121]
	v_mfma_f32_16x16x32_bf16 v[110:113], v[146:149], v[188:191], v[110:113]
	v_mfma_f32_16x16x32_bf16 v[102:105], v[142:145], v[196:199], v[102:105]
	v_mfma_f32_16x16x32_bf16 v[94:97], v[146:149], v[196:199], v[94:97]
	v_mfma_f32_16x16x32_bf16 v[86:89], v[142:145], v[214:217], v[86:89]
	v_mfma_f32_16x16x32_bf16 v[78:81], v[146:149], v[214:217], v[78:81]
	v_mfma_f32_16x16x32_bf16 v[74:77], v[142:145], v[222:225], v[74:77]
	v_mfma_f32_16x16x32_bf16 v[70:73], v[146:149], v[222:225], v[70:73]
	v_mfma_f32_16x16x32_bf16 v[118:121], v[134:137], v[192:195], v[118:121]
	v_mfma_f32_16x16x32_bf16 v[110:113], v[138:141], v[192:195], v[110:113]
	v_mfma_f32_16x16x32_bf16 v[102:105], v[134:137], v[206:209], v[102:105]
	v_mfma_f32_16x16x32_bf16 v[94:97], v[138:141], v[206:209], v[94:97]
	v_mfma_f32_16x16x32_bf16 v[86:89], v[134:137], v[218:221], v[86:89]
	v_mfma_f32_16x16x32_bf16 v[78:81], v[138:141], v[218:221], v[78:81]
	v_mfma_f32_16x16x32_bf16 v[74:77], v[134:137], v[226:229], v[74:77]
	v_mfma_f32_16x16x32_bf16 v[70:73], v[138:141], v[226:229], v[70:73]
	s_barrier
	s_and_b64 vcc, exec, s[6:7]
	s_cbranch_vccnz .LBB0_208
	v_ffbh_u32_e32 v188, v177
	v_min_u32_e32 v190, 32, v188
	v_lshlrev_b64 v[188:189], v190, v[176:177]
	v_min_u32_e32 v188, 1, v188
	v_or_b32_e32 v188, v189, v188
	v_cvt_f32_u32_e32 v188, v188
	v_sub_u32_e32 v189, 32, v190
	v_ldexp_f32 v188, v188, v189
	v_mul_f32_e32 v188, 0x33800000, v188
	v_fmamk_f32 v188, v188, 0x3a000000, v232
	v_rsq_f32_e32 v188, v188
	ds_write_b32 v204, v188
	s_branch .LBB0_208

.LBB0_483:
	s_lshl_b32 s10, s69, 15
	s_mov_b32 s11, s77
	s_lshl_b64 s[10:11], s[10:11], 3
	s_add_u32 s12, s4, s10
	s_addc_u32 s13, s5, s11
	s_add_i32 m0, s41, 0x18000
	v_lshl_add_u64 v[6:7], v[6:7], 0, s[82:83]
	s_waitcnt vmcnt(2)
	s_barrier
	global_load_lds_dwordx4 v[6:7], off
	v_lshl_add_u64 v[6:7], v[8:9], 0, s[82:83]
	s_add_i32 m0, s41, 0x1a000
	s_add_i32 s45, s41, 0x8000
	global_load_lds_dwordx4 v[6:7], off
	v_lshl_add_u64 v[6:7], v[14:15], 0, s[82:83]
	s_mov_b32 m0, s45
	s_add_i32 s46, s41, 0xa000
	global_load_lds_dwordx4 v[6:7], off
	v_lshl_add_u64 v[6:7], v[16:17], 0, s[82:83]
	s_mov_b32 m0, s46
	v_bfe_u32 v8, v4, 4, 2
	global_load_lds_dwordx4 v[6:7], off
	s_add_i32 m0, s41, 0x1c000
	v_lshl_add_u64 v[6:7], v[10:11], 0, s[82:83]
	global_load_lds_dwordx4 v[6:7], off
	v_lshl_add_u64 v[6:7], v[12:13], 0, s[82:83]
	s_add_i32 m0, s41, 0x1e000
	s_lshl_b32 s4, s9, 13
	global_load_lds_dwordx4 v[6:7], off
	v_and_b32_e32 v6, 15, v4
	v_lshlrev_b32_e32 v7, 4, v8
	v_lshl_or_b32 v248, s9, 6, v6
	v_lshl_or_b32 v6, v6, 6, v7
	v_lshlrev_b32_e32 v7, 2, v4
	v_and_b32_e32 v7, 32, v7
	v_bitop3_b32 v9, v6, s4, v7 bitop3:0xde
	s_lshl_b32 s4, s7, 5
	s_and_b32 s14, s4, 0x60
	v_lshlrev_b32_e32 v4, 5, v4
	s_lshl_b32 s4, s14, 7
	v_and_b32_e32 v4, 0x400, v4
	v_bitop3_b32 v249, v6, s4, v7 bitop3:0xde
	v_add_u32_e32 v238, 0x10000, v249
	v_lshl_add_u64 v[6:7], s[12:13], 0, v[4:5]
	v_and_b32_e32 v4, 0x100, v18
	v_lshl_add_u64 v[6:7], v[6:7], 0, v[4:5]
	v_add_u32_e32 v4, v24, v22
	s_lshr_b32 s47, s8, 6
	v_add_lshl_u32 v4, v4, v23, 1
	s_waitcnt vmcnt(6)
	s_add_i32 s48, s47, -2
	v_lshl_add_u64 v[224:225], s[76:77], 0, v[4:5]
	v_add_u32_e32 v4, v21, v19
	v_cndmask_b32_e64 v218, 0.5, 1.0, s[24:25]
	s_cmpk_lt_u32 s6, 0x100
	v_add_lshl_u32 v4, v4, v20, 1
	s_cselect_b64 s[24:25], -1, 0
	s_mov_b32 s49, 0
	v_cmp_eq_u32_e64 s[4:5], 0, v8
	v_cmp_eq_u32_e64 s[6:7], 1, v8
	v_cmp_eq_u32_e64 s[8:9], 2, v8
	v_cmp_eq_u32_e64 s[10:11], 3, v8
	s_ashr_i32 s50, s34, 31
	v_lshl_add_u64 v[220:221], v[6:7], 0, s[72:73]
	v_mov_b32_e32 v222, v218
	v_mov_b32_e32 v223, v218
	v_lshl_or_b32 v250, v8, 3, s14
	v_lshl_add_u64 v[226:227], s[76:77], 0, v[4:5]
	v_add_u32_e32 v251, 0, v9
	v_readlane_b32 s33, v255, 20
	s_mov_b32 s53, s91
	s_barrier
	s_branch .LBB0_486

.LBB0_497:
	s_add_i32 s56, s30, 2
	s_add_u32 s57, s28, 0x80
	s_addc_u32 s31, s29, 0
	s_add_i32 s60, 0, 0x10000
	s_cmp_eq_u32 s48, s30
	s_cselect_b32 s31, s15, s31
	s_cselect_b32 s30, s14, s57
	s_cselect_b32 s59, s27, s55
	s_cselect_b32 s58, s26, s54
	s_add_i32 s57, 0, 0x14000
	ds_read_b128 v[134:137], v238
	ds_read_b128 v[138:141], v238 offset:1024
	ds_read_b128 v[142:145], v238 offset:2048
	ds_read_b128 v[146:149], v238 offset:3072
	ds_read_b128 v[150:153], v238 offset:16384
	ds_read_b128 v[154:157], v238 offset:17408
	ds_read_b128 v[158:161], v238 offset:18432
	ds_read_b128 v[162:165], v238 offset:19456
	s_add_i32 m0, s41, 0xc000
	ds_read_b128 v[166:169], v251
	ds_read_b128 v[170:173], v251 offset:1024
	ds_read_b128 v[174:177], v251 offset:2048
	ds_read_b128 v[178:181], v251 offset:3072
	ds_read_b128 v[182:185], v251 offset:4096
	ds_read_b128 v[186:189], v251 offset:5120
	ds_read_b128 v[190:193], v251 offset:6144
	ds_read_b128 v[194:197], v251 offset:7168
	global_load_lds_dwordx4 v224, s[28:29]
	s_add_i32 m0, s41, 0xe000
	s_nop 0
	global_load_lds_dwordx4 v226, s[28:29]
	s_waitcnt vmcnt(8)
	s_waitcnt lgkmcnt(0)
	s_barrier
	v_mfma_f32_16x16x32_bf16 v[130:133], v[134:137], v[166:169], v[130:133]
	v_mfma_f32_16x16x32_bf16 v[126:129], v[142:145], v[166:169], v[126:129]
	v_mfma_f32_16x16x32_bf16 v[114:117], v[134:137], v[174:177], v[114:117]
	v_mfma_f32_16x16x32_bf16 v[110:113], v[142:145], v[174:177], v[110:113]
	v_mfma_f32_16x16x32_bf16 v[98:101], v[134:137], v[182:185], v[98:101]
	v_mfma_f32_16x16x32_bf16 v[94:97], v[142:145], v[182:185], v[94:97]
	v_mfma_f32_16x16x32_bf16 v[82:85], v[134:137], v[190:193], v[82:85]
	v_mfma_f32_16x16x32_bf16 v[78:81], v[142:145], v[190:193], v[78:81]
	v_mfma_f32_16x16x32_bf16 v[130:133], v[138:141], v[170:173], v[130:133]
	v_mfma_f32_16x16x32_bf16 v[126:129], v[146:149], v[170:173], v[126:129]
	v_mfma_f32_16x16x32_bf16 v[114:117], v[138:141], v[178:181], v[114:117]
	v_mfma_f32_16x16x32_bf16 v[110:113], v[146:149], v[178:181], v[110:113]
	v_mfma_f32_16x16x32_bf16 v[98:101], v[138:141], v[186:189], v[98:101]
	v_mfma_f32_16x16x32_bf16 v[94:97], v[146:149], v[186:189], v[94:97]
	v_mfma_f32_16x16x32_bf16 v[82:85], v[138:141], v[194:197], v[82:85]
	v_mfma_f32_16x16x32_bf16 v[78:81], v[146:149], v[194:197], v[78:81]
	v_mfma_f32_16x16x32_bf16 v[122:125], v[150:153], v[166:169], v[122:125]
	v_mfma_f32_16x16x32_bf16 v[118:121], v[158:161], v[166:169], v[118:121]
	v_mfma_f32_16x16x32_bf16 v[106:109], v[150:153], v[174:177], v[106:109]
	v_mfma_f32_16x16x32_bf16 v[102:105], v[158:161], v[174:177], v[102:105]
	v_mfma_f32_16x16x32_bf16 v[90:93], v[150:153], v[182:185], v[90:93]
	v_mfma_f32_16x16x32_bf16 v[86:89], v[158:161], v[182:185], v[86:89]
	v_mfma_f32_16x16x32_bf16 v[74:77], v[150:153], v[190:193], v[74:77]
	v_mfma_f32_16x16x32_bf16 v[70:73], v[158:161], v[190:193], v[70:73]
	v_mfma_f32_16x16x32_bf16 v[122:125], v[154:157], v[170:173], v[122:125]
	v_mfma_f32_16x16x32_bf16 v[118:121], v[162:165], v[170:173], v[118:121]
	v_mfma_f32_16x16x32_bf16 v[106:109], v[154:157], v[178:181], v[106:109]
	v_mfma_f32_16x16x32_bf16 v[102:105], v[162:165], v[178:181], v[102:105]
	v_mfma_f32_16x16x32_bf16 v[90:93], v[154:157], v[186:189], v[90:93]
	v_mfma_f32_16x16x32_bf16 v[86:89], v[162:165], v[186:189], v[86:89]
	v_mfma_f32_16x16x32_bf16 v[74:77], v[154:157], v[194:197], v[74:77]
	v_mfma_f32_16x16x32_bf16 v[70:73], v[162:165], v[194:197], v[70:73]
	s_barrier
	s_add_i32 s60, s60, s40
	s_mov_b32 m0, s60
	ds_read_b128 v[166:169], v251 offset:16384
	ds_read_b128 v[170:173], v251 offset:17408
	ds_read_b128 v[174:177], v251 offset:18432
	ds_read_b128 v[178:181], v251 offset:19456
	ds_read_b128 v[182:185], v251 offset:20480
	ds_read_b128 v[186:189], v251 offset:21504
	ds_read_b128 v[190:193], v251 offset:22528
	ds_read_b128 v[194:197], v251 offset:23552
	global_load_lds_dwordx4 v214, s[58:59]
	s_add_i32 m0, s60, 0x2000
	s_add_i32 s57, s57, s40
	global_load_lds_dwordx4 v2, s[58:59]
	s_add_u32 s58, s58, s76
	s_addc_u32 s59, s59, 0
	s_mov_b32 m0, s57
	s_nop 0
	global_load_lds_dwordx4 v214, s[58:59]
	s_add_i32 m0, s57, 0x2000
	s_nop 0
	global_load_lds_dwordx4 v2, s[58:59]
	s_mov_b32 m0, s41
	s_nop 0
	global_load_lds_dwordx4 v216, s[30:31]
	s_mov_b32 m0, s42
	s_nop 0
	global_load_lds_dwordx4 v212, s[30:31]
	s_waitcnt vmcnt(8)
	s_waitcnt lgkmcnt(0)
	s_barrier
	v_mfma_f32_16x16x32_bf16 v[66:69], v[134:137], v[166:169], v[66:69]
	v_mfma_f32_16x16x32_bf16 v[62:65], v[142:145], v[166:169], v[62:65]
	v_mfma_f32_16x16x32_bf16 v[50:53], v[134:137], v[174:177], v[50:53]
	v_mfma_f32_16x16x32_bf16 v[46:49], v[142:145], v[174:177], v[46:49]
	v_mfma_f32_16x16x32_bf16 v[34:37], v[134:137], v[182:185], v[34:37]
	v_mfma_f32_16x16x32_bf16 v[30:33], v[142:145], v[182:185], v[30:33]
	v_mfma_f32_16x16x32_bf16 v[18:21], v[134:137], v[190:193], v[18:21]
	v_mfma_f32_16x16x32_bf16 v[14:17], v[142:145], v[190:193], v[14:17]
	v_mfma_f32_16x16x32_bf16 v[66:69], v[138:141], v[170:173], v[66:69]
	v_mfma_f32_16x16x32_bf16 v[62:65], v[146:149], v[170:173], v[62:65]
	v_mfma_f32_16x16x32_bf16 v[50:53], v[138:141], v[178:181], v[50:53]
	v_mfma_f32_16x16x32_bf16 v[46:49], v[146:149], v[178:181], v[46:49]
	v_mfma_f32_16x16x32_bf16 v[34:37], v[138:141], v[186:189], v[34:37]
	v_mfma_f32_16x16x32_bf16 v[30:33], v[146:149], v[186:189], v[30:33]
	v_mfma_f32_16x16x32_bf16 v[18:21], v[138:141], v[194:197], v[18:21]
	v_mfma_f32_16x16x32_bf16 v[14:17], v[146:149], v[194:197], v[14:17]
	v_mfma_f32_16x16x32_bf16 v[58:61], v[150:153], v[166:169], v[58:61]
	v_mfma_f32_16x16x32_bf16 v[54:57], v[158:161], v[166:169], v[54:57]
	v_mfma_f32_16x16x32_bf16 v[42:45], v[150:153], v[174:177], v[42:45]
	v_mfma_f32_16x16x32_bf16 v[38:41], v[158:161], v[174:177], v[38:41]
	v_mfma_f32_16x16x32_bf16 v[26:29], v[150:153], v[182:185], v[26:29]
	v_mfma_f32_16x16x32_bf16 v[22:25], v[158:161], v[182:185], v[22:25]
	v_mfma_f32_16x16x32_bf16 v[10:13], v[150:153], v[190:193], v[10:13]
	v_mfma_f32_16x16x32_bf16 v[6:9], v[158:161], v[190:193], v[6:9]
	v_mfma_f32_16x16x32_bf16 v[58:61], v[154:157], v[170:173], v[58:61]
	v_mfma_f32_16x16x32_bf16 v[54:57], v[162:165], v[170:173], v[54:57]
	v_mfma_f32_16x16x32_bf16 v[42:45], v[154:157], v[178:181], v[42:45]
	v_mfma_f32_16x16x32_bf16 v[38:41], v[162:165], v[178:181], v[38:41]
	v_mfma_f32_16x16x32_bf16 v[26:29], v[154:157], v[186:189], v[26:29]
	v_mfma_f32_16x16x32_bf16 v[22:25], v[162:165], v[186:189], v[22:25]
	v_mfma_f32_16x16x32_bf16 v[10:13], v[154:157], v[194:197], v[10:13]
	v_mfma_f32_16x16x32_bf16 v[6:9], v[162:165], v[194:197], v[6:9]
	s_barrier
	ds_read_b128 v[134:137], v238 offset:32768
	ds_read_b128 v[138:141], v238 offset:33792
	ds_read_b128 v[142:145], v238 offset:34816
	ds_read_b128 v[146:149], v238 offset:35840
	ds_read_b128 v[150:153], v238 offset:49152
	ds_read_b128 v[154:157], v238 offset:50176
	ds_read_b128 v[158:161], v238 offset:51200
	ds_read_b128 v[162:165], v238 offset:52224
	s_add_u32 s30, s30, s76
	s_addc_u32 s31, s31, 0
	s_mov_b32 m0, s43
	ds_read_b128 v[166:169], v251 offset:32768
	ds_read_b128 v[170:173], v251 offset:33792
	ds_read_b128 v[174:177], v251 offset:34816
	ds_read_b128 v[178:181], v251 offset:35840
	ds_read_b128 v[182:185], v251 offset:36864
	ds_read_b128 v[186:189], v251 offset:37888
	ds_read_b128 v[190:193], v251 offset:38912
	ds_read_b128 v[194:197], v251 offset:39936
	global_load_lds_dwordx4 v216, s[30:31]
	s_mov_b32 m0, s44
	s_nop 0
	global_load_lds_dwordx4 v212, s[30:31]
	s_waitcnt vmcnt(8)
	s_waitcnt lgkmcnt(0)
	s_barrier
	v_mfma_f32_16x16x32_bf16 v[130:133], v[134:137], v[166:169], v[130:133]
	v_mfma_f32_16x16x32_bf16 v[126:129], v[142:145], v[166:169], v[126:129]
	v_mfma_f32_16x16x32_bf16 v[114:117], v[134:137], v[174:177], v[114:117]
	v_mfma_f32_16x16x32_bf16 v[110:113], v[142:145], v[174:177], v[110:113]
	v_mfma_f32_16x16x32_bf16 v[98:101], v[134:137], v[182:185], v[98:101]
	v_mfma_f32_16x16x32_bf16 v[94:97], v[142:145], v[182:185], v[94:97]
	v_mfma_f32_16x16x32_bf16 v[82:85], v[134:137], v[190:193], v[82:85]
	v_mfma_f32_16x16x32_bf16 v[78:81], v[142:145], v[190:193], v[78:81]
	v_mfma_f32_16x16x32_bf16 v[130:133], v[138:141], v[170:173], v[130:133]
	v_mfma_f32_16x16x32_bf16 v[126:129], v[146:149], v[170:173], v[126:129]
	v_mfma_f32_16x16x32_bf16 v[114:117], v[138:141], v[178:181], v[114:117]
	v_mfma_f32_16x16x32_bf16 v[110:113], v[146:149], v[178:181], v[110:113]
	v_mfma_f32_16x16x32_bf16 v[98:101], v[138:141], v[186:189], v[98:101]
	v_mfma_f32_16x16x32_bf16 v[94:97], v[146:149], v[186:189], v[94:97]
	v_mfma_f32_16x16x32_bf16 v[82:85], v[138:141], v[194:197], v[82:85]
	v_mfma_f32_16x16x32_bf16 v[78:81], v[146:149], v[194:197], v[78:81]
	v_mfma_f32_16x16x32_bf16 v[122:125], v[150:153], v[166:169], v[122:125]
	v_mfma_f32_16x16x32_bf16 v[118:121], v[158:161], v[166:169], v[118:121]
	v_mfma_f32_16x16x32_bf16 v[106:109], v[150:153], v[174:177], v[106:109]
	v_mfma_f32_16x16x32_bf16 v[102:105], v[158:161], v[174:177], v[102:105]
	v_mfma_f32_16x16x32_bf16 v[90:93], v[150:153], v[182:185], v[90:93]
	v_mfma_f32_16x16x32_bf16 v[86:89], v[158:161], v[182:185], v[86:89]
	v_mfma_f32_16x16x32_bf16 v[74:77], v[150:153], v[190:193], v[74:77]
	v_mfma_f32_16x16x32_bf16 v[70:73], v[158:161], v[190:193], v[70:73]
	v_mfma_f32_16x16x32_bf16 v[122:125], v[154:157], v[170:173], v[122:125]
	v_mfma_f32_16x16x32_bf16 v[118:121], v[162:165], v[170:173], v[118:121]
	v_mfma_f32_16x16x32_bf16 v[106:109], v[154:157], v[178:181], v[106:109]
	v_mfma_f32_16x16x32_bf16 v[102:105], v[162:165], v[178:181], v[102:105]
	v_mfma_f32_16x16x32_bf16 v[90:93], v[154:157], v[186:189], v[90:93]
	v_mfma_f32_16x16x32_bf16 v[86:89], v[162:165], v[186:189], v[86:89]
	v_mfma_f32_16x16x32_bf16 v[74:77], v[154:157], v[194:197], v[74:77]
	v_mfma_f32_16x16x32_bf16 v[70:73], v[162:165], v[194:197], v[70:73]
	s_barrier
	s_sub_u32 s98, s58, s76
	s_subb_u32 s99, s59, 0
	s_add_u32 s98, s98, 0x80
	s_addc_u32 s99, s99, 0
	s_add_i32 m0, s40, 0x18000
	ds_read_b128 v[166:169], v251 offset:49152
	ds_read_b128 v[170:173], v251 offset:50176
	ds_read_b128 v[174:177], v251 offset:51200
	ds_read_b128 v[178:181], v251 offset:52224
	ds_read_b128 v[182:185], v251 offset:53248
	ds_read_b128 v[186:189], v251 offset:54272
	ds_read_b128 v[190:193], v251 offset:55296
	ds_read_b128 v[194:197], v251 offset:56320
	global_load_lds_dwordx4 v214, s[98:99]
	s_add_i32 m0, s40, 0x1a000
	s_add_u32 s58, s58, 0x80
	s_addc_u32 s59, s59, 0
	global_load_lds_dwordx4 v2, s[98:99]
	s_add_i32 m0, s40, 0x1c000
	s_sub_u32 s30, s30, s76
	s_subb_u32 s31, s31, 0
	global_load_lds_dwordx4 v214, s[58:59]
	s_add_i32 m0, s40, 0x1e000
	s_add_u32 s30, s30, 0x80
	s_addc_u32 s31, s31, 0
	global_load_lds_dwordx4 v2, s[58:59]
	s_mov_b32 m0, s45
	s_nop 0
	global_load_lds_dwordx4 v216, s[30:31]
	s_mov_b32 m0, s46
	s_nop 0
	global_load_lds_dwordx4 v212, s[30:31]
	s_waitcnt vmcnt(8)
	s_waitcnt lgkmcnt(0)
	s_barrier
	v_mfma_f32_16x16x32_bf16 v[66:69], v[134:137], v[166:169], v[66:69]
	v_mfma_f32_16x16x32_bf16 v[62:65], v[142:145], v[166:169], v[62:65]
	v_mfma_f32_16x16x32_bf16 v[50:53], v[134:137], v[174:177], v[50:53]
	v_mfma_f32_16x16x32_bf16 v[46:49], v[142:145], v[174:177], v[46:49]
	v_mfma_f32_16x16x32_bf16 v[34:37], v[134:137], v[182:185], v[34:37]
	v_mfma_f32_16x16x32_bf16 v[30:33], v[142:145], v[182:185], v[30:33]
	v_mfma_f32_16x16x32_bf16 v[18:21], v[134:137], v[190:193], v[18:21]
	v_mfma_f32_16x16x32_bf16 v[14:17], v[142:145], v[190:193], v[14:17]
	v_mfma_f32_16x16x32_bf16 v[66:69], v[138:141], v[170:173], v[66:69]
	v_mfma_f32_16x16x32_bf16 v[62:65], v[146:149], v[170:173], v[62:65]
	v_mfma_f32_16x16x32_bf16 v[50:53], v[138:141], v[178:181], v[50:53]
	v_mfma_f32_16x16x32_bf16 v[46:49], v[146:149], v[178:181], v[46:49]
	v_mfma_f32_16x16x32_bf16 v[34:37], v[138:141], v[186:189], v[34:37]
	v_mfma_f32_16x16x32_bf16 v[30:33], v[146:149], v[186:189], v[30:33]
	v_mfma_f32_16x16x32_bf16 v[18:21], v[138:141], v[194:197], v[18:21]
	v_mfma_f32_16x16x32_bf16 v[14:17], v[146:149], v[194:197], v[14:17]
	v_mfma_f32_16x16x32_bf16 v[58:61], v[150:153], v[166:169], v[58:61]
	v_mfma_f32_16x16x32_bf16 v[54:57], v[158:161], v[166:169], v[54:57]
	v_mfma_f32_16x16x32_bf16 v[42:45], v[150:153], v[174:177], v[42:45]
	v_mfma_f32_16x16x32_bf16 v[38:41], v[158:161], v[174:177], v[38:41]
	v_mfma_f32_16x16x32_bf16 v[26:29], v[150:153], v[182:185], v[26:29]
	v_mfma_f32_16x16x32_bf16 v[22:25], v[158:161], v[182:185], v[22:25]
	v_mfma_f32_16x16x32_bf16 v[10:13], v[150:153], v[190:193], v[10:13]
	v_mfma_f32_16x16x32_bf16 v[6:9], v[158:161], v[190:193], v[6:9]
	v_mfma_f32_16x16x32_bf16 v[58:61], v[154:157], v[170:173], v[58:61]
	v_mfma_f32_16x16x32_bf16 v[54:57], v[162:165], v[170:173], v[54:57]
	v_mfma_f32_16x16x32_bf16 v[42:45], v[154:157], v[178:181], v[42:45]
	v_mfma_f32_16x16x32_bf16 v[38:41], v[162:165], v[178:181], v[38:41]
	v_mfma_f32_16x16x32_bf16 v[26:29], v[154:157], v[186:189], v[26:29]
	v_mfma_f32_16x16x32_bf16 v[22:25], v[162:165], v[186:189], v[22:25]
	v_mfma_f32_16x16x32_bf16 v[10:13], v[154:157], v[194:197], v[10:13]
	v_mfma_f32_16x16x32_bf16 v[6:9], v[162:165], v[194:197], v[6:9]
	s_barrier
	s_add_u32 s28, s28, 0x100
	s_addc_u32 s29, s29, 0
	s_add_u32 s54, s54, 0x100
	s_addc_u32 s55, s55, 0
	s_cmp_ge_u32 s56, s47
	s_mov_b32 s30, s56
	s_cbranch_scc0 .LBB0_497
	s_and_b64 vcc, exec, s[24:25]
	s_cbranch_vccz .LBB0_500
	s_barrier
